# DN: ph_d stores its ycat rows with the nt (streaming) policy, on top of C6+N3
# speedup vs baseline: 1.0071x; 1.0071x over previous
.LBB0_21:
	s_or_b64 exec, exec, s[10:11]
	global_load_dwordx4 v[32:35], v[12:13], off offset:16
	global_load_dwordx4 v[36:39], v[12:13], off
	s_waitcnt vmcnt(0)
	v_lshlrev_b32_e32 v46, 16, v5
	v_and_b32_e32 v47, 0xffff0000, v5
	v_lshlrev_b32_e32 v52, 16, v4
	v_and_b32_e32 v53, 0xffff0000, v4
	s_waitcnt vmcnt(3)
	v_lshlrev_b32_e32 v4, 16, v8
	v_and_b32_e32 v5, 0xffff0000, v8
	v_lshlrev_b32_e32 v48, 16, v9
	v_and_b32_e32 v49, 0xffff0000, v9
	v_pk_add_f32 v[4:5], v[52:53], v[4:5]
	v_lshlrev_b32_e32 v26, 16, v7
	v_and_b32_e32 v27, 0xffff0000, v7
	v_lshlrev_b32_e32 v44, 16, v6
	v_and_b32_e32 v45, 0xffff0000, v6
	v_lshlrev_b32_e32 v6, 16, v10
	v_and_b32_e32 v7, 0xffff0000, v10
	s_waitcnt vmcnt(2)
	v_lshlrev_b32_e32 v10, 16, v2
	v_pk_add_f32 v[46:47], v[46:47], v[48:49]
	v_pk_mul_f32 v[8:9], v[4:5], v[4:5]
	v_lshlrev_b32_e32 v40, 16, v11
	v_and_b32_e32 v41, 0xffff0000, v11
	v_and_b32_e32 v11, 0xffff0000, v2
	v_mul_f32_e32 v2, 0xbfb8aa3b, v10
	v_pk_mul_f32 v[50:51], v[46:47], v[46:47]
	v_add_f32_e32 v8, v8, v9
	v_pk_add_f32 v[6:7], v[44:45], v[6:7]
	v_exp_f32_e32 v31, v2
	v_mul_f32_e32 v2, 0xbfb8aa3b, v11
	v_add_f32_e32 v8, v50, v8
	v_pk_add_f32 v[26:27], v[26:27], v[40:41]
	v_lshlrev_b32_e32 v40, 16, v3
	v_and_b32_e32 v41, 0xffff0000, v3
	v_exp_f32_e32 v45, v2
	v_pk_mul_f32 v[2:3], v[6:7], v[6:7]
	v_add_f32_e32 v8, v51, v8
	v_add_f32_e32 v2, v2, v8
	v_pk_mul_f32 v[42:43], v[26:27], v[26:27]
	v_add_f32_e32 v2, v3, v2
	v_lshlrev_b32_e32 v48, 16, v1
	v_add_f32_e32 v2, v42, v2
	v_and_b32_e32 v49, 0xffff0000, v1
	v_mul_f32_e32 v1, 0xbfb8aa3b, v48
	v_add_f32_e32 v3, v43, v2
	v_exp_f32_e32 v1, v1
	ds_bpermute_b32 v8, v21, v3
	v_add_f32_e32 v31, 1.0, v31
	v_mul_f32_e32 v2, 0xbfb8aa3b, v49
	v_add_f32_e32 v1, 1.0, v1
	v_rcp_f32_e32 v44, v31
	v_add_f32_e32 v31, 1.0, v45
	v_exp_f32_e32 v9, v2
	v_rcp_f32_e32 v2, v1
	s_waitcnt lgkmcnt(0)
	v_add_f32_e32 v1, v3, v8
	v_rcp_f32_e32 v45, v31
	ds_bpermute_b32 v31, v28, v1
	v_add_f32_e32 v3, 1.0, v9
	v_lshlrev_b32_e32 v8, 16, v0
	v_and_b32_e32 v9, 0xffff0000, v0
	v_mul_f32_e32 v42, 0xbfb8aa3b, v9
	s_waitcnt lgkmcnt(0)
	v_add_f32_e32 v0, v1, v31
	ds_bpermute_b32 v1, v29, v0
	v_mul_f32_e32 v31, 0xbfb8aa3b, v8
	v_exp_f32_e32 v31, v31
	v_exp_f32_e32 v42, v42
	v_rcp_f32_e32 v3, v3
	s_waitcnt lgkmcnt(0)
	v_add_f32_e32 v43, v0, v1
	ds_bpermute_b32 v50, v30, v43
	v_add_f32_e32 v0, 1.0, v31
	v_add_f32_e32 v1, 1.0, v42
	v_rcp_f32_e32 v0, v0
	v_rcp_f32_e32 v1, v1
	s_waitcnt lgkmcnt(0)
	v_add_f32_e32 v31, v43, v50
	v_fmamk_f32 v31, v31, 0x3c000000, v234
	v_mul_f32_e32 v42, 0x4b800000, v31
	v_cmp_gt_f32_e32 vcc, s25, v31
	v_pk_mul_f32 v[0:1], v[0:1], v[8:9]
	v_pk_mul_f32 v[2:3], v[2:3], v[48:49]
	v_cndmask_b32_e32 v31, v31, v42, vcc
	v_rsq_f32_e32 v31, v31
	v_pk_mul_f32 v[10:11], v[44:45], v[10:11]
	v_readlane_b32 s0, v253, 45
	v_readlane_b32 s1, v253, 46
	v_mul_f32_e32 v8, 0x45800000, v31
	v_cndmask_b32_e32 v8, v31, v8, vcc
	v_pk_mul_f32 v[4:5], v[4:5], v[8:9] op_sel_hi:[1,0]
	v_add_u32_e32 v20, s94, v20
	s_waitcnt vmcnt(0)
	v_pk_mul_f32 v[4:5], v[36:37], v[4:5]
	s_nop 0
	v_pk_mul_f32 v[0:1], v[0:1], v[4:5]
	v_pk_mul_f32 v[4:5], v[46:47], v[8:9] op_sel_hi:[1,0]
	v_cvt_pk_bf16_f32 v0, v0, v1
	v_pk_mul_f32 v[4:5], v[38:39], v[4:5]
	s_nop 0
	v_pk_mul_f32 v[2:3], v[2:3], v[4:5]
	v_mul_f32_e32 v4, 0xbfb8aa3b, v40
	v_mul_f32_e32 v5, 0xbfb8aa3b, v41
	v_exp_f32_e32 v4, v4
	v_exp_f32_e32 v5, v5
	v_cvt_pk_bf16_f32 v1, v2, v3
	v_pk_mul_f32 v[2:3], v[6:7], v[8:9] op_sel_hi:[1,0]
	v_add_f32_e32 v4, 1.0, v4
	v_add_f32_e32 v5, 1.0, v5
	v_rcp_f32_e32 v4, v4
	v_rcp_f32_e32 v5, v5
	v_pk_mul_f32 v[6:7], v[26:27], v[8:9] op_sel_hi:[1,0]
	v_pk_mul_f32 v[2:3], v[32:33], v[2:3]
	v_pk_mul_f32 v[6:7], v[34:35], v[6:7]
	v_pk_mul_f32 v[4:5], v[4:5], v[40:41]
	v_pk_mul_f32 v[2:3], v[10:11], v[2:3]
	v_pk_mul_f32 v[4:5], v[4:5], v[6:7]
	v_cvt_pk_bf16_f32 v2, v2, v3
	v_cvt_pk_bf16_f32 v3, v4, v5
	v_lshl_add_u64 v[4:5], s[0:1], 0, v[24:25]
	v_readlane_b32 s0, v254, 60
	v_lshl_add_u64 v[4:5], v[22:23], 1, v[4:5]
	v_lshl_add_u64 v[4:5], v[4:5], 0, v[128:129]
	v_add_u32_e32 v15, s0, v15
	s_mov_b32 s0, 0x8fff
	v_cmp_lt_i32_e32 vcc, s0, v15
	s_or_b64 s[4:5], vcc, s[4:5]
	global_store_dwordx4 v[4:5], v[0:3], off offset:1024 nt
	v_readlane_b32 s1, v254, 61
	s_andn2_b64 exec, exec, s[4:5]
	s_cbranch_execz .LBB0_24
.LBB0_22:
	s_mov_b32 s0, 0x55555556
	v_mul_hi_i32 v0, v15, s0
	v_lshrrev_b32_e32 v1, 31, v0
	v_add_u32_e32 v26, v0, v1
	s_movk_i32 s0, 0xfa00
	v_mad_u64_u32 v[22:23], s[0:1], v26, s0, v[20:21]
	v_ashrrev_i32_e32 v23, 31, v22
	s_movk_i32 s0, 0x600
	v_mad_i64_i32 v[0:1], s[0:1], v26, s0, v[22:23]
	v_or_b32_e32 v0, v0, v14
	v_readlane_b32 s0, v251, 23
	v_lshlrev_b64 v[0:1], 1, v[0:1]
	v_readlane_b32 s1, v251, 24
	v_lshl_add_u32 v24, v26, 1, v26
	v_ashrrev_i32_e32 v27, 31, v26
	v_lshl_add_u64 v[2:3], s[0:1], 0, v[0:1]
	v_readlane_b32 s0, v251, 27
	v_readlane_b32 s1, v251, 28
	global_load_dwordx4 v[4:7], v[2:3], off
	s_nop 0
	v_lshl_add_u64 v[0:1], s[0:1], 0, v[0:1]
	global_load_dwordx4 v[8:11], v[0:1], off
	v_mov_b64_e32 v[0:1], s[80:81]
	s_movk_i32 s0, 0x3800
	v_mad_i64_i32 v[0:1], s[0:1], v26, s0, v[0:1]
	v_lshl_add_u64 v[0:1], v[22:23], 1, v[0:1]
	v_lshl_add_u64 v[0:1], v[0:1], 0, v[128:129]
	v_add_co_u32_e32 v0, vcc, 0xd27a000, v0
	s_nop 1
	v_addc_co_u32_e32 v1, vcc, 0, v1, vcc
	global_load_dwordx4 v[0:3], v[0:1], off offset:3072
	v_cmp_eq_u32_e32 vcc, v24, v15
	v_lshlrev_b64 v[24:25], 12, v[26:27]
	s_and_saveexec_b64 s[10:11], vcc
	s_cbranch_execz .LBB0_21
	v_lshlrev_b64 v[26:27], 10, v[26:27]
	v_lshl_add_u64 v[26:27], v[18:19], 0, v[26:27]
	global_load_dwordx4 v[32:35], v[26:27], off
	v_lshl_add_u64 v[26:27], v[16:17], 0, v[24:25]
	s_waitcnt vmcnt(0)
	global_store_dwordx4 v[26:27], v[32:35], off nt
	s_branch .LBB0_21
